# attention / retention phases: one static s_setprio 1 for waves 4-7 (reset at the phase end)
# baseline (speedup 1.0000x reference)
.LBB0_1042:
	s_waitcnt lgkmcnt(0)
	v_readfirstlane_b32 s4, v2
	v_readfirstlane_b32 s5, v3
	v_readfirstlane_b32 s6, v4
	v_readfirstlane_b32 s7, v5
	v_min_u32_e32 v8, 47, v198
	v_lshlrev_b32_e32 v8, 3, v8
	s_nop 3
	global_load_dwordx2 v[10:11], v8, s[4:5]
	global_load_dwordx2 v[12:13], v8, s[6:7]
	s_waitcnt vmcnt(0)
	v_max_f32_e64 v1, |v10|, |v11|
	v_max_f32_e64 v7, |v12|, |v13|
	s_nop 1
	v_max_f32_dpp v1, v1, v1 quad_perm:[1,0,3,2] row_mask:0xf bank_mask:0xf bound_ctrl:1
	v_max_f32_dpp v7, v7, v7 quad_perm:[1,0,3,2] row_mask:0xf bank_mask:0xf bound_ctrl:1
	s_nop 1
	v_max_f32_dpp v1, v1, v1 quad_perm:[2,3,0,1] row_mask:0xf bank_mask:0xf bound_ctrl:1
	v_max_f32_dpp v7, v7, v7 quad_perm:[2,3,0,1] row_mask:0xf bank_mask:0xf bound_ctrl:1
	s_nop 1
	v_max_f32_dpp v1, v1, v1 row_half_mirror row_mask:0xf bank_mask:0xf bound_ctrl:1
	v_max_f32_dpp v7, v7, v7 row_half_mirror row_mask:0xf bank_mask:0xf bound_ctrl:1
	s_nop 1
	v_max_f32_dpp v1, v1, v1 row_mirror row_mask:0xf bank_mask:0xf bound_ctrl:1
	v_max_f32_dpp v7, v7, v7 row_mirror row_mask:0xf bank_mask:0xf bound_ctrl:1
	s_nop 1
	v_readlane_b32 s98, v1, 0
	v_readlane_b32 s99, v1, 16
	v_readlane_b32 s100, v1, 32
	v_readlane_b32 s101, v1, 48
	s_nop 1
	v_mov_b32_e32 v1, s98
	v_max_f32_e32 v1, s99, v1
	v_max_f32_e32 v1, s100, v1
	v_max_f32_e32 v1, s101, v1
	s_nop 1
	v_readlane_b32 s98, v7, 0
	v_readlane_b32 s99, v7, 16
	v_readlane_b32 s100, v7, 32
	v_readlane_b32 s101, v7, 48
	s_nop 1
	v_mov_b32_e32 v7, s98
	v_max_f32_e32 v7, s99, v7
	v_max_f32_e32 v7, s100, v7
	v_max_f32_e32 v7, s101, v7
	s_cmpk_lt_u32 s33, 0x100
	s_cbranch_scc1 .Lprio6_skip
	s_setprio 1
.Lprio6_skip:
	s_add_u32 s38, s34, 0x3d28000
	s_addc_u32 s39, s35, 0
	s_add_u32 s12, s34, 0xb4e8000
	s_addc_u32 s13, s35, 0
	s_add_u32 s14, s34, 0xbf68000
	s_addc_u32 s15, s35, 0
	s_cmpk_lg_i32 s56, 0x100
	s_cselect_b64 s[4:5], -1, 0
	s_add_i32 s2, 0, 0x10400
	v_lshl_add_u32 v5, v198, 2, s2
	s_lshl_b32 s2, s30, 5
	v_and_b32_e32 v104, 48, v198
	v_mov_b32_e32 v105, 0
	v_mul_f32_e32 v1, 0x411cc471, v1
	s_and_b32 s18, s2, 0xe0
	v_lshl_add_u64 v[2:3], s[34:35], 0, v[104:105]
	s_mov_b64 s[2:3], 0xabe8000
	v_mul_f32_e32 v1, v1, v7
	v_lshl_add_u64 v[106:107], v[2:3], 0, s[2:3]
	s_mov_b32 s2, 0x15555556
	v_or_b32_e32 v7, 0x200, v0
	v_or_b32_e32 v6, 0x400, v0
	v_mul_hi_u32 v144, v0, s2
	v_mul_hi_u32 v145, v7, s2
	v_mul_hi_u32 v146, v6, s2
	v_mul_u32_u24_e32 v2, 12, v144
	v_mul_u32_u24_e32 v4, 12, v145
	v_mul_u32_u24_e32 v9, 12, v146
	v_sub_u32_e32 v3, v0, v2
	v_sub_u32_e32 v8, v7, v4
	v_sub_u32_e32 v9, v6, v9
	v_lshlrev_b32_e32 v14, 3, v0
	s_add_i32 s2, 0, 0x15400
	v_mul_f32_e32 v140, 0x3fb8aa3b, v1
	s_ashr_i32 s17, s30, 3
	v_and_b32_e32 v1, 15, v0
	v_lshrrev_b32_e32 v103, 4, v198
	v_lshlrev_b32_e32 v2, 3, v3
	v_lshlrev_b32_e32 v4, 3, v8
	v_lshlrev_b32_e32 v6, 3, v9
	v_lshrrev_b32_e32 v99, 3, v0
	v_and_b32_e32 v101, 7, v0
	v_lshrrev_b32_e32 v147, 3, v7
	v_bitop3_b32 v3, v144, v3, 15 bitop3:0x6c
	v_bitop3_b32 v8, v145, v8, 15 bitop3:0x6c
	v_bitop3_b32 v9, v146, v9, 15 bitop3:0x6c
	s_movk_i32 s22, 0xa0
	v_and_b32_e32 v142, 24, v14
	v_mov_b32_e32 v14, s2
	s_and_b32 s19, s17, -2
	v_lshl_add_u32 v7, v144, 8, 0
	v_lshlrev_b32_e32 v3, 4, v3
	v_lshl_add_u32 v10, v145, 8, 0
	v_lshlrev_b32_e32 v8, 4, v8
	v_lshl_add_u32 v11, v146, 8, 0
	v_lshlrev_b32_e32 v9, 4, v9
	v_mad_u32_u24 v12, v99, s22, 0
	v_lshlrev_b32_e32 v102, 4, v101
	v_mad_u32_u24 v13, v147, s22, 0
	v_lshlrev_b32_e32 v98, 2, v103
	v_bfe_u32 v141, v0, 2, 2
	v_mad_u32_u24 v15, v99, s22, v14
	v_mad_u32_u24 v14, v147, s22, v14
	v_lshl_add_u32 v149, v198, 4, 0
	s_lshl_b32 s6, s68, 7
	v_lshl_add_u32 v16, v1, 2, 0
	v_lshlrev_b32_e32 v118, 1, v2
	v_mbcnt_lo_u32_b32 v2, -1, 0
	s_mov_b32 s16, 0x3fb8aa3b
	s_mov_b32 s7, 0
	s_addk_i32 s19, 0x100
	s_and_b32 s20, s17, -16
	v_lshlrev_b32_e32 v138, 3, v103
	s_movk_i32 s21, 0x600
	v_mul_u32_u24_e32 v108, 0x600, v144
	v_mov_b32_e32 v109, v105
	v_mul_u32_u24_e32 v110, 0x600, v145
	v_mov_b32_e32 v111, v105
	v_mul_u32_u24_e32 v112, 0x600, v146
	v_mov_b32_e32 v113, v105
	v_lshlrev_b32_e32 v114, 10, v99
	v_mov_b32_e32 v115, v105
	v_lshlrev_b32_e32 v100, 3, v101
	v_lshlrev_b32_e32 v116, 10, v147
	v_mov_b32_e32 v117, v105
	v_or_b32_e32 v139, 4, v103
	v_or_b32_e32 v148, 8, v103
	v_cmp_gt_u32_e64 s[2:3], 16, v198
	s_lshl_b32 s23, s68, 13
	v_or_b32_e32 v150, v141, v98
	v_add_u32_e32 v151, 0x10400, v16
	v_add_u32_e32 v152, 0x400, v149
	v_add_u32_e32 v153, 0x800, v149
	v_add_u32_e32 v154, 0xc00, v149
	v_add_u32_e32 v155, 0x1000, v149
	v_add_u32_e32 v156, 0x10440, v16
	v_add_u32_e32 v157, 0x1400, v149
	v_lshlrev_b32_e32 v120, 1, v4
	v_lshlrev_b32_e32 v122, 1, v6
	s_mov_b32 s24, 0x30000
	s_mov_b32 s25, 0x20000
	v_add_u32_e32 v158, v15, v102
	v_add_u32_e32 v159, v14, v102
	v_add_u32_e32 v160, v7, v3
	v_add_u32_e32 v161, v10, v8
	v_add_u32_e32 v162, v11, v9
	v_add_u32_e32 v163, v12, v102
	v_add_u32_e32 v164, v13, v102
	v_mbcnt_hi_u32_b32 v143, -1, v2
	v_add_u32_e32 v165, s6, v5
	s_mov_b32 s10, 0
	s_mov_b32 s26, 0
	s_branch .LBB0_1045

.LBB0_1106:
	s_setprio 0
	s_cmp_lt_i32 s59, 8
	s_barrier
	s_cbranch_scc1 .LBB0_1160
	s_waitcnt vmcnt(0)
	s_barrier
	s_and_saveexec_b64 s[2:3], s[0:1]
	s_cbranch_execz .LBB0_1159
	s_waitcnt vmcnt(0) lgkmcnt(0)
	v_mov_b32_e32 v241, 0

.LBB0_2792:
	v_readfirstlane_b32 s8, v2
	v_readfirstlane_b32 s9, v3
	v_readfirstlane_b32 s10, v4
	v_readfirstlane_b32 s11, v5
	v_lshlrev_b32_e32 v9, 2, v198
	s_nop 4
	global_load_dword v6, v9, s[8:9]
	global_load_dword v7, v9, s[10:11]
	s_waitcnt vmcnt(0)
	v_and_b32_e32 v6, 0x7fffffff, v6
	v_and_b32_e32 v7, 0x7fffffff, v7
	s_nop 1
	v_max_f32_dpp v6, v6, v6 quad_perm:[1,0,3,2] row_mask:0xf bank_mask:0xf bound_ctrl:1
	v_max_f32_dpp v7, v7, v7 quad_perm:[1,0,3,2] row_mask:0xf bank_mask:0xf bound_ctrl:1
	s_nop 1
	v_max_f32_dpp v6, v6, v6 quad_perm:[2,3,0,1] row_mask:0xf bank_mask:0xf bound_ctrl:1
	v_max_f32_dpp v7, v7, v7 quad_perm:[2,3,0,1] row_mask:0xf bank_mask:0xf bound_ctrl:1
	s_nop 1
	v_max_f32_dpp v6, v6, v6 row_half_mirror row_mask:0xf bank_mask:0xf bound_ctrl:1
	v_max_f32_dpp v7, v7, v7 row_half_mirror row_mask:0xf bank_mask:0xf bound_ctrl:1
	s_nop 1
	v_max_f32_dpp v6, v6, v6 row_mirror row_mask:0xf bank_mask:0xf bound_ctrl:1
	v_max_f32_dpp v7, v7, v7 row_mirror row_mask:0xf bank_mask:0xf bound_ctrl:1
	s_nop 1
	v_readlane_b32 s98, v6, 0
	v_readlane_b32 s99, v6, 16
	v_readlane_b32 s100, v6, 32
	v_readlane_b32 s101, v6, 48
	s_nop 1
	v_mov_b32_e32 v6, s98
	v_max_f32_e32 v6, s99, v6
	v_max_f32_e32 v6, s100, v6
	v_max_f32_e32 v6, s101, v6
	s_nop 1
	v_readlane_b32 s98, v7, 0
	v_readlane_b32 s99, v7, 16
	v_readlane_b32 s100, v7, 32
	v_readlane_b32 s101, v7, 48
	s_nop 1
	v_mov_b32_e32 v7, s98
	v_max_f32_e32 v7, s99, v7
	v_max_f32_e32 v7, s100, v7
	v_max_f32_e32 v7, s101, v7
	s_cmpk_lt_u32 s33, 0x100
	s_cbranch_scc1 .Lprio14_skip
	s_setprio 1
.Lprio14_skip:
	s_add_u32 s14, s2, 0xaa28000
	s_addc_u32 s15, s3, 0
	s_add_u32 s16, s2, 0xa328000
	s_addc_u32 s17, s3, 0
	v_mul_f32_e32 v2, 0x41000000, v6
	s_add_u32 s6, s2, 0xe5a8000
	v_mul_f32_e32 v2, v2, v7
	v_and_b32_e32 v106, 48, v198
	v_mov_b32_e32 v107, 0
	v_or_b32_e32 v6, 0x200, v0
	s_addc_u32 s7, s3, 0
	v_mul_f32_e32 v136, 0x3fb8aa3b, v2
	v_lshl_add_u64 v[2:3], s[2:3], 0, v[106:107]
	s_mov_b64 s[2:3], 0x9d28000
	v_lshrrev_b32_e32 v138, 3, v0
	v_lshrrev_b32_e32 v139, 3, v6
	v_lshrrev_b32_e32 v140, 4, v6
	v_or_b32_e32 v6, 0x600, v0
	v_lshl_add_u64 v[108:109], v[2:3], 0, s[2:3]
	v_lshrrev_b32_e32 v142, 4, v6
	v_lshlrev_b32_e32 v6, 8, v138
	v_lshlrev_b32_e32 v9, 8, v139
	s_add_i32 s2, 0, 0x11400
	v_add_u32_e32 v7, 0, v6
	v_add_u32_e32 v10, 0, v9
	v_lshlrev_b32_e32 v15, 3, v0
	v_add_u32_e32 v6, s2, v6
	v_add_u32_e32 v9, s2, v9
	s_add_i32 s2, 0, 0x19400
	s_add_i32 s8, 0, 0x20400
	v_lshrrev_b32_e32 v137, 4, v198
	v_and_b32_e32 v3, 7, v0
	s_movk_i32 s23, 0x120
	v_and_b32_e32 v145, 24, v15
	v_mov_b32_e32 v15, s2
	v_lshl_add_u32 v5, v198, 2, s8
	s_ashr_i32 s19, s30, 3
	s_lshl_b32 s8, s30, 5
	v_lshlrev_b32_e32 v2, 3, v3
	v_bitop3_b32 v8, v138, v3, 15 bitop3:0x6c
	v_bitop3_b32 v3, v139, v3, 15 bitop3:0x6c
	v_lshlrev_b32_e32 v144, 2, v137
	v_lshrrev_b32_e32 v14, 2, v1
	v_mad_u32_u24 v147, v199, s23, v15
	s_and_b32 s20, s8, 0xe0
	s_and_b32 s21, s19, -2
	v_lshlrev_b32_e32 v4, 3, v1
	v_or_b32_e32 v141, 64, v199
	v_lshlrev_b32_e32 v8, 4, v8
	v_lshlrev_b32_e32 v3, 4, v3
	v_mad_u32_u24 v11, v199, s23, 0
	v_lshlrev_b32_e32 v143, 4, v1
	v_mad_u32_u24 v12, v140, s23, 0
	v_mad_u32_u24 v13, v142, s23, 0
	v_mad_u32_u24 v16, v140, s23, v15
	v_add_u32_e32 v17, 0x4800, v147
	v_mad_u32_u24 v15, v142, s23, v15
	v_lshl_add_u32 v148, v198, 4, 0
	s_lshl_b32 s8, s68, 7
	v_or_b32_e32 v149, v14, v144
	v_lshl_add_u32 v14, v1, 2, 0
	v_lshlrev_b32_e32 v122, 1, v2
	v_mbcnt_lo_u32_b32 v2, -1, 0
	s_mov_b32 s18, 0x3fb8aa3b
	s_mov_b32 s9, 0
	s_addk_i32 s21, 0x100
	s_and_b32 s22, s19, -16
	v_lshlrev_b32_e32 v110, 10, v138
	v_mov_b32_e32 v111, v107
	v_lshlrev_b32_e32 v112, 10, v139
	v_mov_b32_e32 v113, v107
	v_lshlrev_b32_e32 v114, 10, v199
	v_mov_b32_e32 v115, v107
	v_lshlrev_b32_e32 v116, 10, v140
	v_mov_b32_e32 v117, v107
	v_lshlrev_b32_e32 v118, 10, v141
	v_mov_b32_e32 v119, v107
	v_lshlrev_b32_e32 v120, 10, v142
	v_mov_b32_e32 v121, v107
	v_or_b32_e32 v146, 4, v137
	v_cmp_gt_u32_e64 s[2:3], 16, v198
	s_lshl_b32 s24, s68, 14
	v_add_u32_e32 v150, 0x20400, v14
	v_add_u32_e32 v151, 0x400, v148
	v_add_u32_e32 v152, 0x800, v148
	v_add_u32_e32 v153, 0xc00, v148
	v_add_u32_e32 v154, 0x1000, v148
	v_add_u32_e32 v155, 0x20440, v14
	v_add_u32_e32 v156, 0x2400, v148
	v_lshlrev_b32_e32 v124, 1, v4
	v_add_u32_e32 v157, v6, v8
	v_add_u32_e32 v158, v9, v3
	v_add_u32_e32 v159, v16, v143
	v_add_u32_e32 v160, v17, v143
	v_add_u32_e32 v161, v15, v143
	v_add_u32_e32 v162, v7, v8
	v_add_u32_e32 v163, v10, v3
	v_add_u32_e32 v164, v11, v143
	v_add_u32_e32 v165, v12, v143
	v_add_u32_e32 v166, v13, v143
	v_mbcnt_hi_u32_b32 v167, -1, v2
	v_add_u32_e32 v168, s8, v5
	s_mov_b32 s12, 0
	s_mov_b32 s25, 0
	s_branch .LBB0_2795

.LBB0_2844:
	s_setprio 0
	s_cmp_lt_i32 s59, 18
	s_barrier
	s_cbranch_scc1 .LBB0_2898
	s_waitcnt vmcnt(0)
	s_barrier
	s_and_saveexec_b64 s[2:3], s[0:1]
	s_cbranch_execz .LBB0_2897
	s_waitcnt vmcnt(0) lgkmcnt(0)
	v_mov_b32_e32 v241, 0
